# scan phase pipelined: helper waves 4-7 load+prep+derive+M the next chunk (double-buffered derived LDS arrays) while waves 0-3 run the f32-MFMA compute; rendezvous barriers after sub-chunks 1 and 2
# speedup vs baseline: 1.0227x; 1.0004x over previous
.LBB0_672:
	s_add_i32 s22, s65, 1
	s_and_b32 s23, s65, 1
	s_mov_b32 s24, 0
	v_and_b32_e32 v224, 63, v64
	v_and_b32_e32 v233, 15, v224
	v_lshrrev_b32_e32 v234, 4, v224
	s_mov_b32 s98, 0
	s_mov_b32 s99, -1
	s_cmp_lg_u32 s65, 0
	s_cbranch_scc1 .Lmy_ck_nz
	v_mov_b32_e32 v208, 0
	v_mov_b32_e32 v209, 0
	v_mov_b32_e32 v210, 0
	v_mov_b32_e32 v211, 0
	v_mov_b32_e32 v212, 0
	v_mov_b32_e32 v213, 0
	v_mov_b32_e32 v214, 0
	v_mov_b32_e32 v215, 0
	v_mov_b32_e32 v216, 0
	v_mov_b32_e32 v217, 0
	v_mov_b32_e32 v218, 0
	v_mov_b32_e32 v219, 0
	v_mov_b32_e32 v220, 0
	v_mov_b32_e32 v221, 0
	v_mov_b32_e32 v222, 0
	v_mov_b32_e32 v223, 0
.Lmy_ck_nz:
	s_mov_b32 s100, 0xe000
	s_cmp_eq_u32 s23, 0
	s_cselect_b32 s100, 0x1c000, s100
	v_lshl_add_u32 v236, v224, 4, s100
	v_xor_b32_e32 v225, v224, v234
	v_lshl_add_u32 v225, v225, 4, s100
	s_add_i32 s101, s100, 0x2000
	v_lshl_add_u32 v226, v234, 4, s101
	s_add_i32 s101, s100, 0x2600
	v_mov_b32_e32 v72, s101
	v_cmp_eq_u32_e64 s[96:97], 0, v234
	s_add_i32 s101, s100, 0x2500
	v_mov_b32_e32 v73, s101
	s_add_i32 s101, s100, 0x2510
	v_mov_b32_e32 v74, s101
	v_cndmask_b32_e64 v227, v72, v73, s[96:97]
	v_cmp_eq_u32_e64 s[96:97], 1, v234
	s_add_i32 s101, s100, 0x2590
	v_mov_b32_e32 v75, s101
	v_and_b32_e32 v76, 1, v234
	v_cndmask_b32_e64 v228, v72, v74, s[96:97]
	v_cndmask_b32_e64 v229, v72, v75, s[96:97]
	v_lshlrev_b32_e32 v76, 10, v76
	v_lshl_add_u32 v76, v233, 2, v76
	v_add_u32_e32 v76, s62, v76
	s_lshl_b32 s96, s23, 13
	s_add_i32 s96, s96, 0xa000
	v_add_u32_e32 v230, s96, v76
	s_lshl_b32 s96, s23, 13
	s_add_i32 s96, s96, 0x18000
	v_add_u32_e32 v231, s96, v76
	v_add_u32_e32 v232, 48, v224
	v_and_b32_e32 v232, 63, v232
	v_lshlrev_b32_e32 v232, 2, v232
	v_mov_b32_e32 v235, 0
	s_cmp_lg_u32 s65, 0
	s_cbranch_scc1 .Lmy_f_main
	s_bfe_u32 s96, s62, 0x20006
	s_lshl_b32 s100, s96, 11
	v_lshl_add_u32 v72, v224, 2, s100
	s_mul_i32 s97, s96, 0x2700
	s_cmp_gt_u32 s96, 1
	s_cselect_b32 s101, 0x1300, 0
	s_add_i32 s97, s97, s101
	s_add_i32 s97, s97, 0x1c000
	ds_read_b32 v80, v72
	ds_read_b32 v81, v72 offset:256
	ds_read_b32 v82, v72 offset:512
	ds_read_b32 v83, v72 offset:768
	ds_read_b32 v84, v72 offset:1024
	ds_read_b32 v85, v72 offset:1280
	ds_read_b32 v86, v72 offset:1536
	ds_read_b32 v87, v72 offset:1792
	s_cmpk_ge_u32 s62, 0x100
	s_cbranch_scc1 .Lmy_ck_drB_a
	ds_read_b32 v88, v72 offset:8192
	ds_read_b32 v89, v72 offset:8448
	ds_read_b32 v90, v72 offset:8704
	ds_read_b32 v91, v72 offset:8960
	ds_read_b32 v92, v72 offset:9216
	ds_read_b32 v93, v72 offset:9472
	ds_read_b32 v94, v72 offset:9728
	ds_read_b32 v95, v72 offset:9984
	ds_read_b32 v96, v72 offset:32768
	ds_read_b32 v97, v72 offset:33024
	ds_read_b32 v98, v72 offset:33280
	ds_read_b32 v99, v72 offset:33536
	ds_read_b32 v100, v72 offset:33792
	ds_read_b32 v101, v72 offset:34048
	ds_read_b32 v102, v72 offset:34304
	ds_read_b32 v103, v72 offset:34560
	v_and_b32_e32 v74, 3, v224
	v_bfe_u32 v75, v224, 2, 2
	v_lshrrev_b32_e32 v76, 4, v224
	v_lshlrev_b32_e32 v74, 2, v74
	v_lshl_add_u32 v74, v75, 8, v74
	v_lshl_add_u32 v74, v76, 10, v74
	s_add_i32 s100, s97, 0x0
	v_add_u32_e32 v74, s100, v74
	v_xor_b32_e32 v76, 0, v75
	v_xor_b32_e32 v77, 1, v75
	v_xor_b32_e32 v78, 2, v75
	v_xor_b32_e32 v79, 3, v75
	v_lshl_add_u32 v76, v76, 4, v74
	v_lshl_add_u32 v77, v77, 4, v74
	v_lshl_add_u32 v78, v78, 4, v74
	v_lshl_add_u32 v79, v79, 4, v74
	s_waitcnt lgkmcnt(15)
	v_mov_b32_e32 v104, v80
	v_mul_f32_e32 v105, v104, v81
	v_mul_f32_e32 v106, v105, v82
	v_mul_f32_e32 v107, v106, v83
	v_mul_f32_e32 v108, v107, v84
	v_mul_f32_e32 v109, v108, v85
	v_mul_f32_e32 v110, v109, v86
	v_mul_f32_e32 v111, v110, v87
	v_mov_b32_e32 v112, v88
	s_waitcnt lgkmcnt(14)
	v_mul_f32_e32 v113, v104, v89
	s_waitcnt lgkmcnt(13)
	v_mul_f32_e32 v114, v105, v90
	s_waitcnt lgkmcnt(12)
	v_mul_f32_e32 v115, v106, v91
	s_waitcnt lgkmcnt(11)
	v_mul_f32_e32 v116, v107, v92
	s_waitcnt lgkmcnt(10)
	v_mul_f32_e32 v117, v108, v93
	s_waitcnt lgkmcnt(9)
	v_mul_f32_e32 v118, v109, v94
	s_waitcnt lgkmcnt(8)
	v_mul_f32_e32 v119, v110, v95
	s_waitcnt lgkmcnt(7)
	v_mul_f32_e32 v120, v104, v96
	s_waitcnt lgkmcnt(6)
	v_mul_f32_e32 v121, v105, v97
	s_waitcnt lgkmcnt(5)
	v_mul_f32_e32 v122, v106, v98
	s_waitcnt lgkmcnt(4)
	v_mul_f32_e32 v123, v107, v99
	s_waitcnt lgkmcnt(3)
	v_mul_f32_e32 v124, v108, v100
	s_waitcnt lgkmcnt(2)
	v_mul_f32_e32 v125, v109, v101
	s_waitcnt lgkmcnt(1)
	v_mul_f32_e32 v126, v110, v102
	s_waitcnt lgkmcnt(0)
	v_mul_f32_e32 v127, v111, v103
	ds_write_b32 v76, v112
	ds_write_b32 v77, v113
	ds_write_b32 v78, v114
	ds_write_b32 v79, v115
	ds_write_b32 v76, v116 offset:64
	ds_write_b32 v77, v117 offset:64
	ds_write_b32 v78, v118 offset:64
	ds_write_b32 v79, v119 offset:64
	ds_write_b32 v76, v120 offset:128
	ds_write_b32 v77, v121 offset:128
	ds_write_b32 v78, v122 offset:128
	ds_write_b32 v79, v123 offset:128
	ds_write_b32 v76, v124 offset:192
	ds_write_b32 v77, v125 offset:192
	ds_write_b32 v78, v126 offset:192
	ds_write_b32 v79, v127 offset:192
	s_branch .Lmy_ck_drE_a
.Lmy_ck_drB_a:
	s_waitcnt lgkmcnt(0)
	ds_read_b32 v88, v72 offset:16384
	ds_read_b32 v89, v72 offset:16640
	ds_read_b32 v90, v72 offset:16896
	ds_read_b32 v91, v72 offset:17152
	ds_read_b32 v92, v72 offset:17408
	ds_read_b32 v93, v72 offset:17664
	ds_read_b32 v94, v72 offset:17920
	ds_read_b32 v95, v72 offset:18176
	ds_read_b32 v96, v72 offset:24576
	ds_read_b32 v97, v72 offset:24832
	ds_read_b32 v98, v72 offset:25088
	ds_read_b32 v99, v72 offset:25344
	ds_read_b32 v100, v72 offset:25600
	ds_read_b32 v101, v72 offset:25856
	ds_read_b32 v102, v72 offset:26112
	ds_read_b32 v103, v72 offset:26368
	v_and_b32_e32 v74, 15, v224
	v_lshrrev_b32_e32 v76, 4, v224
	v_lshlrev_b32_e32 v74, 4, v74
	v_lshl_add_u32 v74, v76, 10, v74
	s_add_i32 s101, s97, 0x1000
	v_add_u32_e32 v74, s101, v74
	s_add_i32 s101, s97, 0x2000
	v_lshl_add_u32 v75, v224, 2, s101
	v_mov_b32_e32 v104, v80
	v_mul_f32_e32 v105, v104, v81
	v_mul_f32_e32 v106, v105, v82
	v_mul_f32_e32 v107, v106, v83
	v_mul_f32_e32 v108, v107, v84
	v_mul_f32_e32 v109, v108, v85
	v_mul_f32_e32 v110, v109, v86
	v_mul_f32_e32 v111, v110, v87
	v_rcp_f32_e32 v112, v104
	v_rcp_f32_e32 v113, v105
	v_rcp_f32_e32 v114, v106
	v_rcp_f32_e32 v115, v107
	v_rcp_f32_e32 v116, v108
	v_rcp_f32_e32 v117, v109
	v_rcp_f32_e32 v118, v110
	v_rcp_f32_e32 v119, v111
	s_waitcnt lgkmcnt(7)
	v_mul_f32_e32 v120, v112, v96
	s_waitcnt lgkmcnt(6)
	v_mul_f32_e32 v121, v113, v97
	s_waitcnt lgkmcnt(5)
	v_mul_f32_e32 v122, v114, v98
	s_waitcnt lgkmcnt(4)
	v_mul_f32_e32 v123, v115, v99
	s_waitcnt lgkmcnt(3)
	v_mul_f32_e32 v124, v116, v100
	s_waitcnt lgkmcnt(2)
	v_mul_f32_e32 v125, v117, v101
	s_waitcnt lgkmcnt(1)
	v_mul_f32_e32 v126, v118, v102
	s_waitcnt lgkmcnt(0)
	v_mul_f32_e32 v127, v119, v103
	v_mul_f32_e32 v112, v112, v88
	v_mul_f32_e32 v113, v113, v89
	v_mul_f32_e32 v114, v114, v90
	v_mul_f32_e32 v115, v115, v91
	v_mul_f32_e32 v116, v116, v92
	v_mul_f32_e32 v117, v117, v93
	v_mul_f32_e32 v118, v118, v94
	v_mul_f32_e32 v119, v119, v95
	ds_write_b128 v74, v[112:115]
	ds_write_b128 v74, v[116:119] offset:256
	ds_write_b128 v74, v[120:123] offset:512
	ds_write_b128 v74, v[124:127] offset:768
	ds_write_b32 v75, v111
.Lmy_ck_drE_a:
	s_waitcnt lgkmcnt(0)
	s_barrier
	s_cmpk_ge_u32 s62, 0x100
	s_cbranch_scc1 .Lmy_ck_mE_a
	s_bfe_u32 s96, s62, 0x20006
	s_mul_i32 s97, s96, 0x2700
	s_cmp_gt_u32 s96, 1
	s_cselect_b32 s101, 0x1300, 0
	s_add_i32 s97, s97, s101
	s_add_i32 s97, s97, 0x1c000
	s_mov_b32 s96, s97
	v_and_b32_e32 v72, 3, v233
	v_lshrrev_b32_e32 v73, 2, v233
	v_lshlrev_b32_e32 v72, 2, v72
	v_lshl_add_u32 v72, v73, 8, v72
	v_lshl_add_u32 v72, v234, 6, v72
	s_add_i32 s97, s96, 0x1000
	v_add_u32_e32 v78, s97, v72
	v_xor_b32_e32 v79, v224, v234
	v_lshl_add_u32 v79, v79, 4, s96
	ds_read_b128 v[96:99], v79
	ds_read_b128 v[100:103], v79 offset:1024
	ds_read_b128 v[104:107], v79 offset:2048
	ds_read_b128 v[108:111], v79 offset:3072
	ds_read_b32 v80, v78
	ds_read_b32 v81, v78 offset:16
	ds_read_b32 v82, v78 offset:32
	ds_read_b32 v83, v78 offset:48
	ds_read_b32 v84, v78 offset:1024
	ds_read_b32 v85, v78 offset:1040
	ds_read_b32 v86, v78 offset:1056
	ds_read_b32 v87, v78 offset:1072
	ds_read_b32 v88, v78 offset:2048
	ds_read_b32 v89, v78 offset:2064
	ds_read_b32 v90, v78 offset:2080
	ds_read_b32 v91, v78 offset:2096
	ds_read_b32 v92, v78 offset:3072
	ds_read_b32 v93, v78 offset:3088
	ds_read_b32 v94, v78 offset:3104
	ds_read_b32 v95, v78 offset:3120
	v_lshl_add_u32 v74, v224, 2, s96
	ds_write_b32 v74, v235 offset:9728
	v_add_u32_e32 v75, -1, v233
	v_mov_b32_e32 v76, -1
	v_cndmask_b32_e64 v75, v76, v75, s[98:99]
	v_cmp_lt_u32_e64 s[100:101], 7, v233
	v_add_u32_e32 v76, -8, v233
	v_and_b32_e32 v77, 1, v234
	v_cndmask_b32_e64 v75, v75, v76, s[100:101]
	v_lshlrev_b32_e32 v77, 2, v77
	v_sub_u32_e32 v76, v75, v77
	v_lshlrev_b32_e32 v77, 2, v234
	v_sub_u32_e32 v77, v233, v77
	v_add_u32_e32 v77, -1, v77
	s_waitcnt lgkmcnt(15)
	v_mfma_f32_16x16x4_f32 v[244:247], v80, v96, 0
	v_mfma_f32_16x16x4_f32 v[240:243], v81, v97, 0
	s_waitcnt lgkmcnt(14)
	v_mfma_f32_16x16x4_f32 v[244:247], v82, v98, v[244:247]
	s_waitcnt lgkmcnt(13)
	v_mfma_f32_16x16x4_f32 v[240:243], v83, v99, v[240:243]
	s_waitcnt lgkmcnt(12)
	v_mfma_f32_16x16x4_f32 v[244:247], v84, v100, v[244:247]
	s_waitcnt lgkmcnt(11)
	v_mfma_f32_16x16x4_f32 v[240:243], v85, v101, v[240:243]
	s_waitcnt lgkmcnt(10)
	v_mfma_f32_16x16x4_f32 v[244:247], v86, v102, v[244:247]
	s_waitcnt lgkmcnt(9)
	v_mfma_f32_16x16x4_f32 v[240:243], v87, v103, v[240:243]
	s_waitcnt lgkmcnt(8)
	v_mfma_f32_16x16x4_f32 v[244:247], v88, v104, v[244:247]
	s_waitcnt lgkmcnt(7)
	v_mfma_f32_16x16x4_f32 v[240:243], v89, v105, v[240:243]
	s_waitcnt lgkmcnt(6)
	v_mfma_f32_16x16x4_f32 v[244:247], v90, v106, v[244:247]
	s_waitcnt lgkmcnt(5)
	v_mfma_f32_16x16x4_f32 v[240:243], v91, v107, v[240:243]
	s_waitcnt lgkmcnt(4)
	v_mfma_f32_16x16x4_f32 v[244:247], v92, v108, v[244:247]
	s_waitcnt lgkmcnt(3)
	v_mfma_f32_16x16x4_f32 v[240:243], v93, v109, v[240:243]
	s_waitcnt lgkmcnt(2)
	v_mfma_f32_16x16x4_f32 v[244:247], v94, v110, v[244:247]
	s_waitcnt lgkmcnt(1)
	v_mfma_f32_16x16x4_f32 v[240:243], v95, v111, v[240:243]
	s_nop 9
	v_add_f32_e32 v244, v244, v240
	v_add_f32_e32 v245, v245, v241
	v_add_f32_e32 v246, v246, v242
	v_add_f32_e32 v247, v247, v243
	v_cmp_le_i32_e64 s[96:97], 0, v76
	v_cmp_le_i32_e64 s[100:101], 1, v76
	s_nop 0
	v_cndmask_b32_e64 v128, 0, v244, s[96:97]
	v_cndmask_b32_e64 v129, 0, v245, s[100:101]
	v_cmp_le_i32_e64 s[96:97], 2, v76
	v_cmp_le_i32_e64 s[100:101], 3, v76
	s_nop 0
	v_cndmask_b32_e64 v130, 0, v246, s[96:97]
	v_cndmask_b32_e64 v131, 0, v247, s[100:101]
	s_bfe_u32 s96, s62, 0x20006
	s_mul_i32 s97, s96, 0x2700
	s_cmp_gt_u32 s96, 1
	s_cselect_b32 s101, 0x1300, 0
	s_add_i32 s97, s97, s101
	s_add_i32 s97, s97, 0x1c000
	v_xor_b32_e32 v74, v224, v234
	v_lshl_add_u32 v74, v74, 4, s97
	ds_write_b128 v74, v[128:131] offset:8448
	v_lshlrev_b32_e32 v75, 7, v234
	v_lshl_add_u32 v75, v233, 2, v75
	v_add_u32_e32 v75, s97, v75
	v_cmp_le_i32_e64 s[96:97], 0, v77
	v_cmp_le_i32_e64 s[100:101], 1, v77
	s_nop 0
	v_cndmask_b32_e64 v132, 0, v244, s[96:97]
	v_cndmask_b32_e64 v133, 0, v245, s[100:101]
	v_cmp_le_i32_e64 s[96:97], 2, v77
	v_cmp_le_i32_e64 s[100:101], 3, v77
	s_nop 0
	v_cndmask_b32_e64 v134, 0, v246, s[96:97]
	v_cndmask_b32_e64 v135, 0, v247, s[100:101]
	s_mov_b64 exec, 0x00ff00ff
	ds_write_b32 v75, v132 offset:9472
	ds_write_b32 v75, v133 offset:9504
	ds_write_b32 v75, v134 offset:9536
	ds_write_b32 v75, v135 offset:9568
	s_mov_b64 exec, -1

.Lmy_f_main:
	s_cmpk_ge_u32 s62, 0x100
	s_cbranch_scc1 .Lmy_f_hlp
	ds_read_b128 v[80:83], v225 offset:8448
	ds_read_b32 v84, v230
	ds_read_b32 v85, v230 offset:256
	ds_read_b32 v86, v230 offset:512
	ds_read_b32 v87, v230 offset:768
	ds_read_b128 v[88:91], v225
	ds_read_b128 v[92:95], v225 offset:1024
	ds_read_b128 v[96:99], v225 offset:2048
	ds_read_b128 v[100:103], v225 offset:3072
	ds_read_b32 v104, v227 offset:4
	ds_read_b32 v105, v227 offset:8
	ds_read_b32 v106, v227 offset:40
	ds_read_b32 v107, v227 offset:12
	ds_read_b32 v108, v227 offset:44
	ds_read_b32 v109, v227 offset:76
	ds_read_b32 v110, v228
	ds_read_b32 v111, v228 offset:32
	ds_read_b32 v112, v228 offset:64
	ds_read_b32 v113, v228 offset:96
	ds_read_b32 v114, v228 offset:4
	ds_read_b32 v115, v228 offset:36
	ds_read_b32 v116, v228 offset:68
	ds_read_b32 v117, v228 offset:100
	ds_read_b32 v118, v228 offset:8
	ds_read_b32 v119, v228 offset:40
	ds_read_b32 v120, v228 offset:72
	ds_read_b32 v121, v228 offset:104
	ds_read_b32 v122, v228 offset:12
	ds_read_b32 v123, v228 offset:44
	ds_read_b32 v124, v228 offset:76
	ds_read_b32 v125, v228 offset:108
	ds_read_b32 v126, v229 offset:4
	ds_read_b32 v127, v229 offset:8
	ds_read_b32 v128, v229 offset:40
	ds_read_b32 v129, v229 offset:12
	ds_read_b32 v130, v229 offset:44
	ds_read_b32 v131, v229 offset:76
	s_waitcnt lgkmcnt(15)
	v_cndmask_b32_e64 v76, 0, v84, s[98:99]
	v_cndmask_b32_e64 v77, 0, v85, s[98:99]
	v_cndmask_b32_e64 v78, 0, v86, s[98:99]
	v_cndmask_b32_e64 v79, 0, v87, s[98:99]
	v_mfma_f32_16x16x4_f32 v[240:243], v80, v76, 0
	v_mfma_f32_16x16x4_f32 v[240:243], v81, v77, v[240:243]
	v_mfma_f32_16x16x4_f32 v[240:243], v82, v78, v[240:243]
	v_mfma_f32_16x16x4_f32 v[240:243], v83, v79, v[240:243]
	v_mfma_f32_16x16x4_f32 v[240:243], v88, v208, v[240:243]
	ds_read_b128 v[184:187], v236 offset:4096
	ds_read_b128 v[188:191], v236 offset:5120
	v_mfma_f32_16x16x4_f32 v[244:247], v89, v209, 0
	ds_read_b128 v[192:195], v236 offset:6144
	ds_read_b128 v[196:199], v236 offset:7168
	v_mfma_f32_16x16x4_f32 v[240:243], v90, v210, v[240:243]
	ds_read_b128 v[132:135], v225 offset:18432
	ds_read_b32 v136, v230 offset:2048
	ds_read_b32 v137, v230 offset:2304
	v_mfma_f32_16x16x4_f32 v[244:247], v91, v211, v[244:247]
	ds_read_b32 v138, v230 offset:2560
	ds_read_b32 v139, v230 offset:2816
	ds_read_b128 v[140:143], v225 offset:9984
	v_mfma_f32_16x16x4_f32 v[240:243], v92, v212, v[240:243]
	ds_read_b128 v[144:147], v225 offset:11008
	ds_read_b128 v[148:151], v225 offset:12032
	ds_read_b128 v[152:155], v225 offset:13056
	v_mfma_f32_16x16x4_f32 v[244:247], v93, v213, v[244:247]
	ds_read_b32 v156, v227 offset:9988
	ds_read_b32 v157, v227 offset:9992
	ds_read_b32 v158, v227 offset:10024
	v_mfma_f32_16x16x4_f32 v[240:243], v94, v214, v[240:243]
	ds_read_b32 v159, v227 offset:9996
	ds_read_b32 v160, v227 offset:10028
	ds_read_b32 v161, v227 offset:10060
	v_mfma_f32_16x16x4_f32 v[244:247], v95, v215, v[244:247]
	ds_read_b32 v162, v228 offset:9984
	ds_read_b32 v163, v228 offset:10016
	ds_read_b32 v164, v228 offset:10048
	v_mfma_f32_16x16x4_f32 v[240:243], v96, v216, v[240:243]
	ds_read_b32 v165, v228 offset:10080
	ds_read_b32 v166, v228 offset:9988
	ds_read_b32 v167, v228 offset:10020
	v_mfma_f32_16x16x4_f32 v[244:247], v97, v217, v[244:247]
	ds_read_b32 v168, v228 offset:10052
	ds_read_b32 v169, v228 offset:10084
	ds_read_b32 v170, v228 offset:9992
	v_mfma_f32_16x16x4_f32 v[240:243], v98, v218, v[240:243]
	ds_read_b32 v171, v228 offset:10024
	ds_read_b32 v172, v228 offset:10056
	ds_read_b32 v173, v228 offset:10088
	v_mfma_f32_16x16x4_f32 v[244:247], v99, v219, v[244:247]
	ds_read_b32 v174, v228 offset:9996
	ds_read_b32 v175, v228 offset:10028
	ds_read_b32 v176, v228 offset:10060
	v_mfma_f32_16x16x4_f32 v[240:243], v100, v220, v[240:243]
	ds_read_b32 v177, v228 offset:10092
	ds_read_b32 v178, v229 offset:9988
	ds_read_b32 v179, v229 offset:9992
	v_mfma_f32_16x16x4_f32 v[244:247], v101, v221, v[244:247]
	ds_read_b32 v180, v229 offset:10024
	ds_read_b32 v181, v229 offset:9996
	ds_read_b32 v182, v229 offset:10028
	v_mfma_f32_16x16x4_f32 v[240:243], v102, v222, v[240:243]
	ds_read_b32 v183, v229 offset:10060
	v_mfma_f32_16x16x4_f32 v[244:247], v103, v223, v[244:247]
	s_nop 9
	v_add_f32_e32 v240, v240, v244
	v_add_f32_e32 v241, v241, v245
	v_add_f32_e32 v242, v242, v246
	v_add_f32_e32 v243, v243, v247
	v_fmac_f32_e32 v241, v104, v240
	v_fmac_f32_e32 v242, v105, v240
	v_fmac_f32_e32 v242, v106, v241
	v_fmac_f32_e32 v243, v107, v240
	v_fmac_f32_e32 v243, v108, v241
	v_fmac_f32_e32 v243, v109, v242
	ds_bpermute_b32 v204, v232, v240
	ds_bpermute_b32 v205, v232, v241
	ds_bpermute_b32 v206, v232, v242
	ds_bpermute_b32 v207, v232, v243
	ds_read_b128 v[88:91], v226
	ds_read_b128 v[92:95], v226 offset:64
	ds_read_b128 v[96:99], v226 offset:128
	ds_read_b128 v[100:103], v226 offset:192
	s_waitcnt lgkmcnt(15)
	v_cndmask_b32_e64 v76, 0, v136, s[98:99]
	v_cndmask_b32_e64 v77, 0, v137, s[98:99]
	v_cndmask_b32_e64 v78, 0, v138, s[98:99]
	v_cndmask_b32_e64 v79, 0, v139, s[98:99]
	v_mfma_f32_16x16x4_f32 v[72:75], v132, v76, 0
	s_waitcnt lgkmcnt(7)
	v_fmac_f32_e32 v240, v110, v204
	s_waitcnt lgkmcnt(6)
	v_fmac_f32_e32 v240, v111, v205
	s_waitcnt lgkmcnt(5)
	v_fmac_f32_e32 v240, v112, v206
	s_waitcnt lgkmcnt(4)
	v_fmac_f32_e32 v240, v113, v207
	v_fmac_f32_e32 v241, v114, v204
	v_fmac_f32_e32 v241, v115, v205
	v_mfma_f32_16x16x4_f32 v[72:75], v133, v77, v[72:75]
	v_fmac_f32_e32 v241, v116, v206
	v_fmac_f32_e32 v241, v117, v207
	v_fmac_f32_e32 v242, v118, v204
	v_fmac_f32_e32 v242, v119, v205
	v_fmac_f32_e32 v242, v120, v206
	v_fmac_f32_e32 v242, v121, v207
	v_mfma_f32_16x16x4_f32 v[72:75], v134, v78, v[72:75]
	v_fmac_f32_e32 v243, v122, v204
	v_fmac_f32_e32 v243, v123, v205
	v_fmac_f32_e32 v243, v124, v206
	v_fmac_f32_e32 v243, v125, v207
	v_mfma_f32_16x16x4_f32 v[72:75], v135, v79, v[72:75]
	v_fmac_f32_e32 v241, v126, v240
	v_fmac_f32_e32 v242, v127, v240
	v_fmac_f32_e32 v242, v128, v241
	v_fmac_f32_e32 v243, v129, v240
	v_fmac_f32_e32 v243, v130, v241
	v_fmac_f32_e32 v243, v131, v242
	v_cndmask_b32_e64 v200, v240, v84, s[98:99]
	v_cndmask_b32_e64 v201, v241, v85, s[98:99]
	v_cndmask_b32_e64 v202, v242, v86, s[98:99]
	v_cndmask_b32_e64 v203, v243, v87, s[98:99]
	v_cndmask_b32_e64 v252, v240, 0, s[98:99]
	v_cndmask_b32_e64 v253, v241, 0, s[98:99]
	v_cndmask_b32_e64 v254, v242, 0, s[98:99]
	v_cndmask_b32_e64 v255, v243, 0, s[98:99]
	v_mfma_f32_16x16x4_f32 v[208:211], v184, v200, v[208:211]
	v_mfma_f32_16x16x4_f32 v[212:215], v188, v200, v[212:215]
	v_mfma_f32_16x16x4_f32 v[216:219], v192, v200, v[216:219]
	v_mfma_f32_16x16x4_f32 v[220:223], v196, v200, v[220:223]
	v_mfma_f32_16x16x4_f32 v[208:211], v185, v201, v[208:211]
	v_mfma_f32_16x16x4_f32 v[212:215], v189, v201, v[212:215]
	v_mfma_f32_16x16x4_f32 v[216:219], v193, v201, v[216:219]
	v_mfma_f32_16x16x4_f32 v[220:223], v197, v201, v[220:223]
	v_mfma_f32_16x16x4_f32 v[208:211], v186, v202, v[208:211]
	v_mfma_f32_16x16x4_f32 v[212:215], v190, v202, v[212:215]
	v_mfma_f32_16x16x4_f32 v[216:219], v194, v202, v[216:219]
	v_mfma_f32_16x16x4_f32 v[220:223], v198, v202, v[220:223]
	v_mfma_f32_16x16x4_f32 v[208:211], v187, v203, v[208:211]
	v_mfma_f32_16x16x4_f32 v[212:215], v191, v203, v[212:215]
	v_mfma_f32_16x16x4_f32 v[216:219], v195, v203, v[216:219]
	v_mfma_f32_16x16x4_f32 v[220:223], v199, v203, v[220:223]
	v_mfma_f32_16x16x4_f32 v[248:251], v80, v252, v[240:243]
	v_mfma_f32_16x16x4_f32 v[248:251], v81, v253, v[248:251]
	v_mfma_f32_16x16x4_f32 v[248:251], v82, v254, v[248:251]
	v_mfma_f32_16x16x4_f32 v[248:251], v83, v255, v[248:251]
	s_waitcnt lgkmcnt(3)
	s_nop 2
	v_mul_f32_e32 v208, v208, v88
	v_mul_f32_e32 v209, v209, v89
	v_mul_f32_e32 v210, v210, v90
	v_mul_f32_e32 v211, v211, v91
	v_mfma_f32_16x16x4_f32 v[72:75], v140, v208, v[72:75]
	s_waitcnt lgkmcnt(2)
	v_mul_f32_e32 v212, v212, v92
	v_mul_f32_e32 v213, v213, v93
	v_mfma_f32_16x16x4_f32 v[244:247], v141, v209, 0
	v_mul_f32_e32 v214, v214, v94
	v_mul_f32_e32 v215, v215, v95
	v_mfma_f32_16x16x4_f32 v[72:75], v142, v210, v[72:75]
	s_waitcnt lgkmcnt(1)
	v_mul_f32_e32 v216, v216, v96
	v_mul_f32_e32 v217, v217, v97
	v_mfma_f32_16x16x4_f32 v[244:247], v143, v211, v[244:247]
	v_mul_f32_e32 v218, v218, v98
	v_mul_f32_e32 v219, v219, v99
	v_mfma_f32_16x16x4_f32 v[72:75], v144, v212, v[72:75]
	s_waitcnt lgkmcnt(0)
	v_mul_f32_e32 v220, v220, v100
	v_mul_f32_e32 v221, v221, v101
	v_mfma_f32_16x16x4_f32 v[244:247], v145, v213, v[244:247]
	v_mul_f32_e32 v222, v222, v102
	v_mul_f32_e32 v223, v223, v103
	v_mfma_f32_16x16x4_f32 v[72:75], v146, v214, v[72:75]
	s_mov_b64 exec, s[98:99]
	ds_write_b32 v231, v248
	ds_write_b32 v231, v249 offset:256
	ds_write_b32 v231, v250 offset:512
	ds_write_b32 v231, v251 offset:768
	s_mov_b64 exec, -1
	ds_read_b128 v[184:187], v236 offset:14080
	ds_read_b128 v[188:191], v236 offset:15104
	v_mfma_f32_16x16x4_f32 v[244:247], v147, v215, v[244:247]
	ds_read_b128 v[192:195], v236 offset:16128
	ds_read_b128 v[196:199], v236 offset:17152
	v_mfma_f32_16x16x4_f32 v[72:75], v148, v216, v[72:75]
	v_mfma_f32_16x16x4_f32 v[244:247], v149, v217, v[244:247]
	v_mfma_f32_16x16x4_f32 v[72:75], v150, v218, v[72:75]
	v_mfma_f32_16x16x4_f32 v[244:247], v151, v219, v[244:247]
	v_mfma_f32_16x16x4_f32 v[72:75], v152, v220, v[72:75]
	v_mfma_f32_16x16x4_f32 v[244:247], v153, v221, v[244:247]
	v_mfma_f32_16x16x4_f32 v[72:75], v154, v222, v[72:75]
	v_mfma_f32_16x16x4_f32 v[244:247], v155, v223, v[244:247]
	s_nop 9
	v_add_f32_e32 v72, v72, v244
	v_add_f32_e32 v73, v73, v245
	v_add_f32_e32 v74, v74, v246
	v_add_f32_e32 v75, v75, v247
	v_fmac_f32_e32 v73, v156, v72
	v_fmac_f32_e32 v74, v157, v72
	v_fmac_f32_e32 v74, v158, v73
	v_fmac_f32_e32 v75, v159, v72
	v_fmac_f32_e32 v75, v160, v73
	v_fmac_f32_e32 v75, v161, v74
	ds_bpermute_b32 v204, v232, v72
	ds_bpermute_b32 v205, v232, v73
	ds_bpermute_b32 v206, v232, v74
	ds_bpermute_b32 v207, v232, v75
	ds_read_b128 v[140:143], v226 offset:9984
	ds_read_b128 v[144:147], v226 offset:10048
	ds_read_b128 v[148:151], v226 offset:10112
	ds_read_b128 v[152:155], v226 offset:10176
	s_waitcnt lgkmcnt(7)
	v_fmac_f32_e32 v72, v162, v204
	s_waitcnt lgkmcnt(6)
	v_fmac_f32_e32 v72, v163, v205
	s_waitcnt lgkmcnt(5)
	v_fmac_f32_e32 v72, v164, v206
	s_waitcnt lgkmcnt(4)
	v_fmac_f32_e32 v72, v165, v207
	v_fmac_f32_e32 v73, v166, v204
	v_fmac_f32_e32 v73, v167, v205
	v_fmac_f32_e32 v73, v168, v206
	v_fmac_f32_e32 v73, v169, v207
	v_fmac_f32_e32 v74, v170, v204
	v_fmac_f32_e32 v74, v171, v205
	v_fmac_f32_e32 v74, v172, v206
	v_fmac_f32_e32 v74, v173, v207
	v_fmac_f32_e32 v75, v174, v204
	v_fmac_f32_e32 v75, v175, v205
	v_fmac_f32_e32 v75, v176, v206
	v_fmac_f32_e32 v75, v177, v207
	v_fmac_f32_e32 v73, v178, v72
	v_fmac_f32_e32 v74, v179, v72
	v_fmac_f32_e32 v74, v180, v73
	v_fmac_f32_e32 v75, v181, v72
	v_fmac_f32_e32 v75, v182, v73
	v_fmac_f32_e32 v75, v183, v74
	v_cndmask_b32_e64 v200, v72, v136, s[98:99]
	v_cndmask_b32_e64 v201, v73, v137, s[98:99]
	v_cndmask_b32_e64 v202, v74, v138, s[98:99]
	v_cndmask_b32_e64 v203, v75, v139, s[98:99]
	v_cndmask_b32_e64 v252, v72, 0, s[98:99]
	v_cndmask_b32_e64 v253, v73, 0, s[98:99]
	v_cndmask_b32_e64 v254, v74, 0, s[98:99]
	v_cndmask_b32_e64 v255, v75, 0, s[98:99]
	v_mfma_f32_16x16x4_f32 v[208:211], v184, v200, v[208:211]
	v_mfma_f32_16x16x4_f32 v[212:215], v188, v200, v[212:215]
	v_mfma_f32_16x16x4_f32 v[216:219], v192, v200, v[216:219]
	v_mfma_f32_16x16x4_f32 v[220:223], v196, v200, v[220:223]
	v_mfma_f32_16x16x4_f32 v[208:211], v185, v201, v[208:211]
	v_mfma_f32_16x16x4_f32 v[212:215], v189, v201, v[212:215]
	v_mfma_f32_16x16x4_f32 v[216:219], v193, v201, v[216:219]
	v_mfma_f32_16x16x4_f32 v[220:223], v197, v201, v[220:223]
	v_mfma_f32_16x16x4_f32 v[208:211], v186, v202, v[208:211]
	v_mfma_f32_16x16x4_f32 v[212:215], v190, v202, v[212:215]
	v_mfma_f32_16x16x4_f32 v[216:219], v194, v202, v[216:219]
	v_mfma_f32_16x16x4_f32 v[220:223], v198, v202, v[220:223]
	v_mfma_f32_16x16x4_f32 v[208:211], v187, v203, v[208:211]
	v_mfma_f32_16x16x4_f32 v[212:215], v191, v203, v[212:215]
	v_mfma_f32_16x16x4_f32 v[216:219], v195, v203, v[216:219]
	v_mfma_f32_16x16x4_f32 v[220:223], v199, v203, v[220:223]
	v_mfma_f32_16x16x4_f32 v[248:251], v132, v252, v[72:75]
	v_mfma_f32_16x16x4_f32 v[248:251], v133, v253, v[248:251]
	v_mfma_f32_16x16x4_f32 v[248:251], v134, v254, v[248:251]
	v_mfma_f32_16x16x4_f32 v[248:251], v135, v255, v[248:251]
	s_barrier
	s_mov_b32 s100, 0x6100
	s_cmp_eq_u32 s23, 0
	s_cselect_b32 s100, s100, 0x4e00
	v_add_u32_e32 v225, s100, v225
	v_add_u32_e32 v236, s100, v236
	v_add_u32_e32 v226, s100, v226
	v_add_u32_e32 v227, s100, v227
	v_add_u32_e32 v228, s100, v228
	v_add_u32_e32 v229, s100, v229
	ds_read_b128 v[80:83], v225 offset:8448
	ds_read_b32 v84, v230 offset:4096
	ds_read_b32 v85, v230 offset:4352
	ds_read_b32 v86, v230 offset:4608
	ds_read_b32 v87, v230 offset:4864
	ds_read_b128 v[88:91], v225
	ds_read_b128 v[92:95], v225 offset:1024
	ds_read_b128 v[96:99], v225 offset:2048
	ds_read_b128 v[100:103], v225 offset:3072
	ds_read_b32 v104, v227 offset:4
	ds_read_b32 v105, v227 offset:8
	ds_read_b32 v106, v227 offset:40
	ds_read_b32 v107, v227 offset:12
	ds_read_b32 v108, v227 offset:44
	ds_read_b32 v109, v227 offset:76
	ds_read_b32 v110, v228
	ds_read_b32 v111, v228 offset:32
	ds_read_b32 v112, v228 offset:64
	ds_read_b32 v113, v228 offset:96
	ds_read_b32 v114, v228 offset:4
	ds_read_b32 v115, v228 offset:36
	ds_read_b32 v116, v228 offset:68
	ds_read_b32 v117, v228 offset:100
	ds_read_b32 v118, v228 offset:8
	ds_read_b32 v119, v228 offset:40
	ds_read_b32 v120, v228 offset:72
	ds_read_b32 v121, v228 offset:104
	ds_read_b32 v122, v228 offset:12
	ds_read_b32 v123, v228 offset:44
	ds_read_b32 v124, v228 offset:76
	ds_read_b32 v125, v228 offset:108
	ds_read_b32 v126, v229 offset:4
	ds_read_b32 v127, v229 offset:8
	ds_read_b32 v128, v229 offset:40
	ds_read_b32 v129, v229 offset:12
	ds_read_b32 v130, v229 offset:44
	ds_read_b32 v131, v229 offset:76
	s_waitcnt lgkmcnt(15)
	v_cndmask_b32_e64 v76, 0, v84, s[98:99]
	v_cndmask_b32_e64 v77, 0, v85, s[98:99]
	v_cndmask_b32_e64 v78, 0, v86, s[98:99]
	v_cndmask_b32_e64 v79, 0, v87, s[98:99]
	v_mfma_f32_16x16x4_f32 v[240:243], v80, v76, 0
	v_mfma_f32_16x16x4_f32 v[240:243], v81, v77, v[240:243]
	v_mfma_f32_16x16x4_f32 v[240:243], v82, v78, v[240:243]
	v_mfma_f32_16x16x4_f32 v[240:243], v83, v79, v[240:243]
	v_mul_f32_e32 v208, v208, v140
	v_mul_f32_e32 v209, v209, v141
	v_mul_f32_e32 v210, v210, v142
	v_mul_f32_e32 v211, v211, v143
	v_mfma_f32_16x16x4_f32 v[240:243], v88, v208, v[240:243]
	v_mul_f32_e32 v212, v212, v144
	v_mul_f32_e32 v213, v213, v145
	v_mfma_f32_16x16x4_f32 v[244:247], v89, v209, 0
	v_mul_f32_e32 v214, v214, v146
	v_mul_f32_e32 v215, v215, v147
	v_mfma_f32_16x16x4_f32 v[240:243], v90, v210, v[240:243]
	v_mul_f32_e32 v216, v216, v148
	v_mul_f32_e32 v217, v217, v149
	v_mfma_f32_16x16x4_f32 v[244:247], v91, v211, v[244:247]
	v_mul_f32_e32 v218, v218, v150
	v_mul_f32_e32 v219, v219, v151
	v_mfma_f32_16x16x4_f32 v[240:243], v92, v212, v[240:243]
	v_mul_f32_e32 v220, v220, v152
	v_mul_f32_e32 v221, v221, v153
	v_mfma_f32_16x16x4_f32 v[244:247], v93, v213, v[244:247]
	v_mul_f32_e32 v222, v222, v154
	v_mul_f32_e32 v223, v223, v155
	v_mfma_f32_16x16x4_f32 v[240:243], v94, v214, v[240:243]
	s_mov_b64 exec, s[98:99]
	ds_write_b32 v231, v248 offset:2048
	ds_write_b32 v231, v249 offset:2304
	ds_write_b32 v231, v250 offset:2560
	ds_write_b32 v231, v251 offset:2816
	s_mov_b64 exec, -1
	ds_read_b128 v[184:187], v236 offset:4096
	ds_read_b128 v[188:191], v236 offset:5120
	v_mfma_f32_16x16x4_f32 v[244:247], v95, v215, v[244:247]
	ds_read_b128 v[192:195], v236 offset:6144
	ds_read_b128 v[196:199], v236 offset:7168
	v_mfma_f32_16x16x4_f32 v[240:243], v96, v216, v[240:243]
	ds_read_b128 v[132:135], v225 offset:18432
	ds_read_b32 v136, v230 offset:6144
	ds_read_b32 v137, v230 offset:6400
	ds_read_b32 v138, v230 offset:6656
	ds_read_b32 v139, v230 offset:6912
	v_mfma_f32_16x16x4_f32 v[244:247], v97, v217, v[244:247]
	ds_read_b128 v[140:143], v225 offset:9984
	ds_read_b128 v[144:147], v225 offset:11008
	ds_read_b128 v[148:151], v225 offset:12032
	ds_read_b128 v[152:155], v225 offset:13056
	ds_read_b32 v156, v227 offset:9988
	v_mfma_f32_16x16x4_f32 v[240:243], v98, v218, v[240:243]
	ds_read_b32 v157, v227 offset:9992
	ds_read_b32 v158, v227 offset:10024
	ds_read_b32 v159, v227 offset:9996
	ds_read_b32 v160, v227 offset:10028
	ds_read_b32 v161, v227 offset:10060
	v_mfma_f32_16x16x4_f32 v[244:247], v99, v219, v[244:247]
	ds_read_b32 v162, v228 offset:9984
	ds_read_b32 v163, v228 offset:10016
	ds_read_b32 v164, v228 offset:10048
	ds_read_b32 v165, v228 offset:10080
	ds_read_b32 v166, v228 offset:9988
	v_mfma_f32_16x16x4_f32 v[240:243], v100, v220, v[240:243]
	ds_read_b32 v167, v228 offset:10020
	ds_read_b32 v168, v228 offset:10052
	ds_read_b32 v169, v228 offset:10084
	ds_read_b32 v170, v228 offset:9992
	ds_read_b32 v171, v228 offset:10024
	v_mfma_f32_16x16x4_f32 v[244:247], v101, v221, v[244:247]
	ds_read_b32 v172, v228 offset:10056
	ds_read_b32 v173, v228 offset:10088
	ds_read_b32 v174, v228 offset:9996
	ds_read_b32 v175, v228 offset:10028
	ds_read_b32 v176, v228 offset:10060
	v_mfma_f32_16x16x4_f32 v[240:243], v102, v222, v[240:243]
	ds_read_b32 v177, v228 offset:10092
	ds_read_b32 v178, v229 offset:9988
	ds_read_b32 v179, v229 offset:9992
	ds_read_b32 v180, v229 offset:10024
	ds_read_b32 v181, v229 offset:9996
	v_mfma_f32_16x16x4_f32 v[244:247], v103, v223, v[244:247]
	ds_read_b32 v182, v229 offset:10028
	ds_read_b32 v183, v229 offset:10060
	s_nop 7
	v_add_f32_e32 v240, v240, v244
	v_add_f32_e32 v241, v241, v245
	v_add_f32_e32 v242, v242, v246
	v_add_f32_e32 v243, v243, v247
	v_fmac_f32_e32 v241, v104, v240
	v_fmac_f32_e32 v242, v105, v240
	v_fmac_f32_e32 v242, v106, v241
	v_fmac_f32_e32 v243, v107, v240
	v_fmac_f32_e32 v243, v108, v241
	v_fmac_f32_e32 v243, v109, v242
	ds_bpermute_b32 v204, v232, v240
	ds_bpermute_b32 v205, v232, v241
	ds_bpermute_b32 v206, v232, v242
	ds_bpermute_b32 v207, v232, v243
	ds_read_b128 v[88:91], v226
	ds_read_b128 v[92:95], v226 offset:64
	ds_read_b128 v[96:99], v226 offset:128
	ds_read_b128 v[100:103], v226 offset:192
	s_waitcnt lgkmcnt(15)
	v_cndmask_b32_e64 v76, 0, v136, s[98:99]
	v_cndmask_b32_e64 v77, 0, v137, s[98:99]
	v_cndmask_b32_e64 v78, 0, v138, s[98:99]
	v_cndmask_b32_e64 v79, 0, v139, s[98:99]
	v_mfma_f32_16x16x4_f32 v[72:75], v132, v76, 0
	s_waitcnt lgkmcnt(7)
	v_fmac_f32_e32 v240, v110, v204
	s_waitcnt lgkmcnt(6)
	v_fmac_f32_e32 v240, v111, v205
	s_waitcnt lgkmcnt(5)
	v_fmac_f32_e32 v240, v112, v206
	s_waitcnt lgkmcnt(4)
	v_fmac_f32_e32 v240, v113, v207
	v_fmac_f32_e32 v241, v114, v204
	v_fmac_f32_e32 v241, v115, v205
	v_mfma_f32_16x16x4_f32 v[72:75], v133, v77, v[72:75]
	v_fmac_f32_e32 v241, v116, v206
	v_fmac_f32_e32 v241, v117, v207
	v_fmac_f32_e32 v242, v118, v204
	v_fmac_f32_e32 v242, v119, v205
	v_fmac_f32_e32 v242, v120, v206
	v_fmac_f32_e32 v242, v121, v207
	v_mfma_f32_16x16x4_f32 v[72:75], v134, v78, v[72:75]
	v_fmac_f32_e32 v243, v122, v204
	v_fmac_f32_e32 v243, v123, v205
	v_fmac_f32_e32 v243, v124, v206
	v_fmac_f32_e32 v243, v125, v207
	v_mfma_f32_16x16x4_f32 v[72:75], v135, v79, v[72:75]
	v_fmac_f32_e32 v241, v126, v240
	v_fmac_f32_e32 v242, v127, v240
	v_fmac_f32_e32 v242, v128, v241
	v_fmac_f32_e32 v243, v129, v240
	v_fmac_f32_e32 v243, v130, v241
	v_fmac_f32_e32 v243, v131, v242
	v_cndmask_b32_e64 v200, v240, v84, s[98:99]
	v_cndmask_b32_e64 v201, v241, v85, s[98:99]
	v_cndmask_b32_e64 v202, v242, v86, s[98:99]
	v_cndmask_b32_e64 v203, v243, v87, s[98:99]
	v_cndmask_b32_e64 v252, v240, 0, s[98:99]
	v_cndmask_b32_e64 v253, v241, 0, s[98:99]
	v_cndmask_b32_e64 v254, v242, 0, s[98:99]
	v_cndmask_b32_e64 v255, v243, 0, s[98:99]
	v_mfma_f32_16x16x4_f32 v[208:211], v184, v200, v[208:211]
	v_mfma_f32_16x16x4_f32 v[212:215], v188, v200, v[212:215]
	v_mfma_f32_16x16x4_f32 v[216:219], v192, v200, v[216:219]
	v_mfma_f32_16x16x4_f32 v[220:223], v196, v200, v[220:223]
	v_mfma_f32_16x16x4_f32 v[208:211], v185, v201, v[208:211]
	v_mfma_f32_16x16x4_f32 v[212:215], v189, v201, v[212:215]
	v_mfma_f32_16x16x4_f32 v[216:219], v193, v201, v[216:219]
	v_mfma_f32_16x16x4_f32 v[220:223], v197, v201, v[220:223]
	v_mfma_f32_16x16x4_f32 v[208:211], v186, v202, v[208:211]
	v_mfma_f32_16x16x4_f32 v[212:215], v190, v202, v[212:215]
	v_mfma_f32_16x16x4_f32 v[216:219], v194, v202, v[216:219]
	v_mfma_f32_16x16x4_f32 v[220:223], v198, v202, v[220:223]
	v_mfma_f32_16x16x4_f32 v[208:211], v187, v203, v[208:211]
	v_mfma_f32_16x16x4_f32 v[212:215], v191, v203, v[212:215]
	v_mfma_f32_16x16x4_f32 v[216:219], v195, v203, v[216:219]
	v_mfma_f32_16x16x4_f32 v[220:223], v199, v203, v[220:223]
	v_mfma_f32_16x16x4_f32 v[248:251], v80, v252, v[240:243]
	v_mfma_f32_16x16x4_f32 v[248:251], v81, v253, v[248:251]
	v_mfma_f32_16x16x4_f32 v[248:251], v82, v254, v[248:251]
	v_mfma_f32_16x16x4_f32 v[248:251], v83, v255, v[248:251]
	s_barrier
	s_waitcnt lgkmcnt(3)
	s_nop 1
	v_mul_f32_e32 v208, v208, v88
	v_mul_f32_e32 v209, v209, v89
	v_mul_f32_e32 v210, v210, v90
	v_mul_f32_e32 v211, v211, v91
	v_mfma_f32_16x16x4_f32 v[72:75], v140, v208, v[72:75]
	s_waitcnt lgkmcnt(2)
	v_mul_f32_e32 v212, v212, v92
	v_mul_f32_e32 v213, v213, v93
	v_mfma_f32_16x16x4_f32 v[244:247], v141, v209, 0
	v_mul_f32_e32 v214, v214, v94
	v_mul_f32_e32 v215, v215, v95
	v_mfma_f32_16x16x4_f32 v[72:75], v142, v210, v[72:75]
	s_waitcnt lgkmcnt(1)
	v_mul_f32_e32 v216, v216, v96
	v_mul_f32_e32 v217, v217, v97
	v_mfma_f32_16x16x4_f32 v[244:247], v143, v211, v[244:247]
	v_mul_f32_e32 v218, v218, v98
	v_mul_f32_e32 v219, v219, v99
	v_mfma_f32_16x16x4_f32 v[72:75], v144, v212, v[72:75]
	s_waitcnt lgkmcnt(0)
	v_mul_f32_e32 v220, v220, v100
	v_mul_f32_e32 v221, v221, v101
	v_mfma_f32_16x16x4_f32 v[244:247], v145, v213, v[244:247]
	v_mul_f32_e32 v222, v222, v102
	v_mul_f32_e32 v223, v223, v103
	v_mfma_f32_16x16x4_f32 v[72:75], v146, v214, v[72:75]
	s_mov_b64 exec, s[98:99]
	ds_write_b32 v231, v248 offset:4096
	ds_write_b32 v231, v249 offset:4352
	ds_write_b32 v231, v250 offset:4608
	ds_write_b32 v231, v251 offset:4864
	s_mov_b64 exec, -1
	ds_read_b128 v[184:187], v236 offset:14080
	ds_read_b128 v[188:191], v236 offset:15104
	v_mfma_f32_16x16x4_f32 v[244:247], v147, v215, v[244:247]
	ds_read_b128 v[192:195], v236 offset:16128
	ds_read_b128 v[196:199], v236 offset:17152
	v_mfma_f32_16x16x4_f32 v[72:75], v148, v216, v[72:75]
	v_mfma_f32_16x16x4_f32 v[244:247], v149, v217, v[244:247]
	v_mfma_f32_16x16x4_f32 v[72:75], v150, v218, v[72:75]
	v_mfma_f32_16x16x4_f32 v[244:247], v151, v219, v[244:247]
	v_mfma_f32_16x16x4_f32 v[72:75], v152, v220, v[72:75]
	v_mfma_f32_16x16x4_f32 v[244:247], v153, v221, v[244:247]
	v_mfma_f32_16x16x4_f32 v[72:75], v154, v222, v[72:75]
	v_mfma_f32_16x16x4_f32 v[244:247], v155, v223, v[244:247]
	s_nop 9
	v_add_f32_e32 v72, v72, v244
	v_add_f32_e32 v73, v73, v245
	v_add_f32_e32 v74, v74, v246
	v_add_f32_e32 v75, v75, v247
	v_fmac_f32_e32 v73, v156, v72
	v_fmac_f32_e32 v74, v157, v72
	v_fmac_f32_e32 v74, v158, v73
	v_fmac_f32_e32 v75, v159, v72
	v_fmac_f32_e32 v75, v160, v73
	v_fmac_f32_e32 v75, v161, v74
	ds_bpermute_b32 v204, v232, v72
	ds_bpermute_b32 v205, v232, v73
	ds_bpermute_b32 v206, v232, v74
	ds_bpermute_b32 v207, v232, v75
	ds_read_b128 v[140:143], v226 offset:9984
	ds_read_b128 v[144:147], v226 offset:10048
	ds_read_b128 v[148:151], v226 offset:10112
	ds_read_b128 v[152:155], v226 offset:10176
	s_waitcnt lgkmcnt(7)
	v_fmac_f32_e32 v72, v162, v204
	s_waitcnt lgkmcnt(6)
	v_fmac_f32_e32 v72, v163, v205
	s_waitcnt lgkmcnt(5)
	v_fmac_f32_e32 v72, v164, v206
	s_waitcnt lgkmcnt(4)
	v_fmac_f32_e32 v72, v165, v207
	v_fmac_f32_e32 v73, v166, v204
	v_fmac_f32_e32 v73, v167, v205
	v_fmac_f32_e32 v73, v168, v206
	v_fmac_f32_e32 v73, v169, v207
	v_fmac_f32_e32 v74, v170, v204
	v_fmac_f32_e32 v74, v171, v205
	v_fmac_f32_e32 v74, v172, v206
	v_fmac_f32_e32 v74, v173, v207
	v_fmac_f32_e32 v75, v174, v204
	v_fmac_f32_e32 v75, v175, v205
	v_fmac_f32_e32 v75, v176, v206
	v_fmac_f32_e32 v75, v177, v207
	v_fmac_f32_e32 v73, v178, v72
	v_fmac_f32_e32 v74, v179, v72
	v_fmac_f32_e32 v74, v180, v73
	v_fmac_f32_e32 v75, v181, v72
	v_fmac_f32_e32 v75, v182, v73
	v_fmac_f32_e32 v75, v183, v74
	v_cndmask_b32_e64 v200, v72, v136, s[98:99]
	v_cndmask_b32_e64 v201, v73, v137, s[98:99]
	v_cndmask_b32_e64 v202, v74, v138, s[98:99]
	v_cndmask_b32_e64 v203, v75, v139, s[98:99]
	v_cndmask_b32_e64 v252, v72, 0, s[98:99]
	v_cndmask_b32_e64 v253, v73, 0, s[98:99]
	v_cndmask_b32_e64 v254, v74, 0, s[98:99]
	v_cndmask_b32_e64 v255, v75, 0, s[98:99]
	v_mfma_f32_16x16x4_f32 v[208:211], v184, v200, v[208:211]
	v_mfma_f32_16x16x4_f32 v[212:215], v188, v200, v[212:215]
	v_mfma_f32_16x16x4_f32 v[216:219], v192, v200, v[216:219]
	v_mfma_f32_16x16x4_f32 v[220:223], v196, v200, v[220:223]
	v_mfma_f32_16x16x4_f32 v[208:211], v185, v201, v[208:211]
	v_mfma_f32_16x16x4_f32 v[212:215], v189, v201, v[212:215]
	v_mfma_f32_16x16x4_f32 v[216:219], v193, v201, v[216:219]
	v_mfma_f32_16x16x4_f32 v[220:223], v197, v201, v[220:223]
	v_mfma_f32_16x16x4_f32 v[208:211], v186, v202, v[208:211]
	v_mfma_f32_16x16x4_f32 v[212:215], v190, v202, v[212:215]
	v_mfma_f32_16x16x4_f32 v[216:219], v194, v202, v[216:219]
	v_mfma_f32_16x16x4_f32 v[220:223], v198, v202, v[220:223]
	v_mfma_f32_16x16x4_f32 v[208:211], v187, v203, v[208:211]
	v_mfma_f32_16x16x4_f32 v[212:215], v191, v203, v[212:215]
	v_mfma_f32_16x16x4_f32 v[216:219], v195, v203, v[216:219]
	v_mfma_f32_16x16x4_f32 v[220:223], v199, v203, v[220:223]
	v_mfma_f32_16x16x4_f32 v[248:251], v132, v252, v[72:75]
	v_mfma_f32_16x16x4_f32 v[248:251], v133, v253, v[248:251]
	v_mfma_f32_16x16x4_f32 v[248:251], v134, v254, v[248:251]
	v_mfma_f32_16x16x4_f32 v[248:251], v135, v255, v[248:251]
	s_waitcnt lgkmcnt(3)
	s_nop 2
	v_mul_f32_e32 v208, v208, v140
	v_mul_f32_e32 v209, v209, v141
	v_mul_f32_e32 v210, v210, v142
	v_mul_f32_e32 v211, v211, v143
	s_waitcnt lgkmcnt(2)
	v_mul_f32_e32 v212, v212, v144
	v_mul_f32_e32 v213, v213, v145
	v_mul_f32_e32 v214, v214, v146
	v_mul_f32_e32 v215, v215, v147
	s_waitcnt lgkmcnt(1)
	v_mul_f32_e32 v216, v216, v148
	v_mul_f32_e32 v217, v217, v149
	v_mul_f32_e32 v218, v218, v150
	v_mul_f32_e32 v219, v219, v151
	s_waitcnt lgkmcnt(0)
	v_mul_f32_e32 v220, v220, v152
	v_mul_f32_e32 v221, v221, v153
	v_mul_f32_e32 v222, v222, v154
	v_mul_f32_e32 v223, v223, v155
	s_mov_b64 exec, s[98:99]
	ds_write_b32 v231, v248 offset:6144
	ds_write_b32 v231, v249 offset:6400
	ds_write_b32 v231, v250 offset:6656
	ds_write_b32 v231, v251 offset:6912
	s_mov_b64 exec, -1
	s_branch .LBB0_655
.Lmy_f_hlp:
	s_cmp_eq_u32 s65, 63
	s_cbranch_scc0 .Lmy_f_hl2
	s_barrier
	s_barrier
	s_branch .LBB0_655
.Lmy_f_hl2:
	v_subrev_u32_e32 v70, 16, v70
	v_add_u32_e32 v71, 16, v71
	v_add_u32_e32 v21, 64, v70
	v_subrev_u32_e32 v140, 64, v71
	v_cndmask_b32_e64 v146, v140, v21, s[4:5]
	v_ashrrev_i32_e32 v147, 31, v146
	v_lshl_add_u64 v[158:159], v[146:147], 0, s[40:41]
	v_mad_u64_u32 v[160:161], s[96:97], v158, s56, v[50:51]
	v_mad_i32_i24 v161, v159, s56, v161
	global_load_dwordx2 v[140:141], v[160:161], off
	v_mov_b32_e32 v144, v20
	v_mov_b32_e32 v145, v20
	v_cmp_lt_i32_e64 s[96:97], 0, v146
	v_mov_b64_e32 v[142:143], v[144:145]
	s_and_saveexec_b64 s[24:25], s[96:97]
	s_cbranch_execz .Lmy_f_l659
	v_add_co_u32_e32 v142, vcc, 0xfffff000, v160
	s_nop 1
	v_addc_co_u32_e32 v143, vcc, -1, v161, vcc
	global_load_dwordx2 v[142:143], v[142:143], off offset:-2048
.Lmy_f_l659:
	s_or_b64 exec, exec, s[24:25]
	v_cmp_gt_i32_e64 s[24:25], s3, v146
	s_and_saveexec_b64 s[54:55], s[24:25]
	s_cbranch_execz .Lmy_f_l661
	v_add_co_u32_e32 v144, vcc, 0x1000, v160
	s_nop 1
	v_addc_co_u32_e32 v145, vcc, 0, v161, vcc
	global_load_dwordx2 v[144:145], v[144:145], off offset:2048
.Lmy_f_l661:
	s_or_b64 exec, exec, s[54:55]
	global_load_dwordx2 v[146:147], v[160:161], off offset:2048
	v_mov_b32_e32 v21, v20
	v_mov_b64_e32 v[148:149], v[20:21]
	s_and_saveexec_b64 s[54:55], s[96:97]
	s_cbranch_execz .Lmy_f_l663
	global_load_dwordx2 v[148:149], v[160:161], off offset:-4096
.Lmy_f_l663:
	s_or_b64 exec, exec, s[54:55]
	v_mov_b64_e32 v[150:151], v[20:21]
	s_and_saveexec_b64 s[54:55], s[24:25]
	s_cbranch_execz .Lmy_f_l665
	v_add_co_u32_e32 v150, vcc, 0x2000, v160
	s_nop 1
	v_addc_co_u32_e32 v151, vcc, 0, v161, vcc
	global_load_dwordx2 v[150:151], v[150:151], off
.Lmy_f_l665:
	s_or_b64 exec, exec, s[54:55]
	v_add_co_u32_e32 v152, vcc, 0x1000, v160
	v_mov_b32_e32 v21, v20
	s_nop 0
	v_addc_co_u32_e32 v153, vcc, 0, v161, vcc
	global_load_dwordx2 v[152:153], v[152:153], off
	v_mov_b64_e32 v[154:155], v[20:21]
	s_and_saveexec_b64 s[54:55], s[96:97]
	s_cbranch_execz .Lmy_f_l667
	global_load_dwordx2 v[154:155], v[160:161], off offset:-2048
.Lmy_f_l667:
	s_or_b64 exec, exec, s[54:55]
	v_mov_b64_e32 v[156:157], v[20:21]
	s_and_saveexec_b64 s[96:97], s[24:25]
	s_cbranch_execz .Lmy_f_l669
	v_add_co_u32_e32 v156, vcc, 0x2000, v160
	s_nop 1
	v_addc_co_u32_e32 v157, vcc, 0, v161, vcc
	global_load_dwordx2 v[156:157], v[156:157], off offset:2048
.Lmy_f_l669:
	s_or_b64 exec, exec, s[96:97]
	v_lshlrev_b64 v[158:159], 13, v[158:159]
	v_lshl_add_u64 v[158:159], v[52:53], 0, v[158:159]
	v_add_co_u32_e32 v160, vcc, 0x1000, v158
	s_nop 1
	v_addc_co_u32_e32 v161, vcc, 0, v159, vcc
	global_load_dwordx2 v[158:159], v[158:159], off
	s_nop 0
	global_load_dwordx2 v[160:161], v[160:161], off
	v_add_u32_e32 v70, 16, v70
	v_subrev_u32_e32 v71, 16, v71
	s_andn2_b64 vcc, exec, s[50:51]
	s_cbranch_vccnz .LBB0_655
	s_waitcnt vmcnt(15)
	v_lshlrev_b32_e32 v72, 16, v28
	v_and_b32_e32 v73, 0xffff0000, v28
	v_lshlrev_b32_e32 v76, 16, v30
	v_and_b32_e32 v77, 0xffff0000, v30
	v_lshlrev_b32_e32 v74, 16, v26
	v_and_b32_e32 v75, 0xffff0000, v26
	v_pk_add_f32 v[72:73], v[72:73], v[76:77]
	s_waitcnt vmcnt(13)
	v_lshlrev_b32_e32 v78, 16, v42
	v_pk_fma_f32 v[72:73], v[72:73], 0.5, v[74:75] op_sel_hi:[1,0,1] neg_lo:[0,0,1] neg_hi:[0,0,1]
	v_and_b32_e32 v79, 0xffff0000, v42
	v_pk_fma_f32 v[72:73], v[0:1], v[72:73], v[74:75]
	v_lshlrev_b32_e32 v74, 16, v40
	v_and_b32_e32 v75, 0xffff0000, v40
	v_lshlrev_b32_e32 v76, 16, v38
	v_and_b32_e32 v77, 0xffff0000, v38
	v_pk_add_f32 v[74:75], v[74:75], v[78:79]
	s_waitcnt vmcnt(12)
	v_cvt_f32_f16_e32 v21, v44
	v_pk_fma_f32 v[74:75], v[74:75], 0.5, v[76:77] op_sel_hi:[1,0,1] neg_lo:[0,0,1] neg_hi:[0,0,1]
	v_lshlrev_b32_e32 v80, 16, v31
	v_pk_fma_f32 v[76:77], v[8:9], v[74:75], v[76:77]
	v_lshlrev_b32_e32 v74, 16, v29
	v_and_b32_e32 v75, 0xffff0000, v29
	v_and_b32_e32 v81, 0xffff0000, v31
	v_lshlrev_b32_e32 v78, 16, v27
	v_and_b32_e32 v79, 0xffff0000, v27
	v_pk_add_f32 v[74:75], v[74:75], v[80:81]
	v_cvt_f32_f16_sdwa v84, v44 dst_sel:DWORD dst_unused:UNUSED_PAD src0_sel:WORD_1
	v_pk_fma_f32 v[74:75], v[74:75], 0.5, v[78:79] op_sel_hi:[1,0,1] neg_lo:[0,0,1] neg_hi:[0,0,1]
	v_lshlrev_b32_e32 v82, 16, v43
	v_pk_fma_f32 v[74:75], v[2:3], v[74:75], v[78:79]
	v_lshlrev_b32_e32 v78, 16, v41
	v_and_b32_e32 v79, 0xffff0000, v41
	v_and_b32_e32 v83, 0xffff0000, v43
	v_cvt_f32_f16_e32 v88, v45
	v_lshlrev_b32_e32 v80, 16, v39
	v_and_b32_e32 v81, 0xffff0000, v39
	v_pk_add_f32 v[78:79], v[78:79], v[82:83]
	v_mul_f32_e32 v21, 0xbf1b4598, v21
	v_pk_fma_f32 v[78:79], v[78:79], 0.5, v[80:81] op_sel_hi:[1,0,1] neg_lo:[0,0,1] neg_hi:[0,0,1]
	v_mul_f32_e32 v21, 0x3fb8aa3b, v21
	v_cvt_f32_f16_sdwa v89, v45 dst_sel:DWORD dst_unused:UNUSED_PAD src0_sel:WORD_1
	v_pk_fma_f32 v[78:79], v[10:11], v[78:79], v[80:81]
	v_exp_f32_e32 v80, v21
	v_mul_f32_e32 v21, 0xbf1b4598, v84
	v_mul_f32_e32 v21, 0x3fb8aa3b, v21
	v_lshlrev_b32_e32 v82, 16, v34
	v_and_b32_e32 v83, 0xffff0000, v34
	v_lshlrev_b32_e32 v86, 16, v36
	v_and_b32_e32 v87, 0xffff0000, v36
	v_exp_f32_e32 v81, v21
	v_lshlrev_b32_e32 v84, 16, v32
	v_and_b32_e32 v85, 0xffff0000, v32
	v_pk_add_f32 v[82:83], v[82:83], v[86:87]
	v_mul_f32_e32 v21, 0xbf1b4598, v88
	v_pk_fma_f32 v[82:83], v[82:83], 0.5, v[84:85] op_sel_hi:[1,0,1] neg_lo:[0,0,1] neg_hi:[0,0,1]
	v_mul_f32_e32 v21, 0x3fb8aa3b, v21
	v_pk_fma_f32 v[96:97], v[4:5], v[82:83], v[84:85]
	v_exp_f32_e32 v82, v21
	v_mul_f32_e32 v21, 0xbf1b4598, v89
	v_lshlrev_b32_e32 v84, 16, v35
	v_and_b32_e32 v85, 0xffff0000, v35
	v_lshlrev_b32_e32 v88, 16, v37
	v_and_b32_e32 v89, 0xffff0000, v37
	v_lshlrev_b32_e32 v86, 16, v33
	v_and_b32_e32 v87, 0xffff0000, v33
	v_pk_add_f32 v[84:85], v[84:85], v[88:89]
	s_waitcnt vmcnt(11)
	v_cvt_f32_f16_sdwa v93, v46 dst_sel:DWORD dst_unused:UNUSED_PAD src0_sel:WORD_1
	v_pk_fma_f32 v[84:85], v[84:85], 0.5, v[86:87] op_sel_hi:[1,0,1] neg_lo:[0,0,1] neg_hi:[0,0,1]
	v_cvt_f32_f16_e32 v92, v46
	v_pk_fma_f32 v[94:95], v[6:7], v[84:85], v[86:87]
	v_pk_mul_f32 v[84:85], v[12:13], v[96:97]
	v_pk_mul_f32 v[88:89], v[14:15], v[94:95]
	v_pk_mul_f32 v[86:87], v[84:85], v[84:85]
	v_pk_mul_f32 v[90:91], v[88:89], v[88:89]
	v_add_f32_e32 v83, v86, v87
	v_add_f32_e32 v83, v90, v83
	v_add_f32_e32 v83, v91, v83
	v_cvt_f32_f16_sdwa v99, v47 dst_sel:DWORD dst_unused:UNUSED_PAD src0_sel:WORD_1
	v_cvt_f32_f16_e32 v98, v47
	v_add_f32_dpp v83, v83, v83 quad_perm:[1,0,3,2] row_mask:0xf bank_mask:0xf bound_ctrl:1
	v_mul_f32_e32 v21, 0x3fb8aa3b, v21
	s_bitcmp1_b32 s22, 0
	v_add_f32_dpp v83, v83, v83 quad_perm:[2,3,0,1] row_mask:0xf bank_mask:0xf bound_ctrl:1
	s_cselect_b32 s23, 0x2000, 0
	s_nop 0
	v_add_f32_dpp v83, v83, v83 row_half_mirror row_mask:0xf bank_mask:0xf bound_ctrl:1
	s_nop 1
	v_add_f32_dpp v83, v83, v83 row_mirror row_mask:0xf bank_mask:0xf bound_ctrl:1
	v_max_f32_e32 v83, 0x179abe15, v83
	v_rsq_f32_e32 v86, v83
	v_exp_f32_e32 v83, v21
	v_add_u32_e32 v21, s23, v67
	v_pk_mul_f32 v[90:91], v[84:85], v[86:87] op_sel_hi:[1,0]
	v_pk_mul_f32 v[100:101], v[88:89], v[86:87] op_sel_hi:[1,0]
	v_xor_b32_e32 v85, 0x80000000, v91
	v_xor_b32_e32 v84, 0x80000000, v90
	v_pk_mul_f32 v[88:89], v[90:91], v[92:93]
	v_pk_mul_f32 v[90:91], v[100:101], v[98:99]
	v_pk_add_f32 v[92:93], v[92:93], -1.0 op_sel_hi:[1,0]
	v_pk_add_f32 v[98:99], v[98:99], -1.0 op_sel_hi:[1,0]
	v_pk_fma_f32 v[92:93], v[16:17], v[92:93], 1.0 op_sel_hi:[1,1,0]
	v_pk_fma_f32 v[98:99], v[18:19], v[98:99], 1.0 op_sel_hi:[1,1,0]
	v_xor_b32_e32 v86, 0x80000000, v100
	v_xor_b32_e32 v87, 0x80000000, v101
	v_pk_mul_f32 v[94:95], v[94:95], v[98:99]
	v_pk_mul_f32 v[92:93], v[96:97], v[92:93]
	ds_write_b128 v67, v[80:83]
	ds_write_b128 v67, v[84:87] offset:8192
	ds_write_b128 v67, v[88:91] offset:16384
	ds_write_b128 v67, v[92:95] offset:24576
	ds_write_b128 v67, v[72:75] offset:32768
	ds_write_b128 v21, v[76:79] offset:40960
	v_add_u32_e32 v67, 0xfffff000, v67
	s_waitcnt vmcnt(0)
	v_lshlrev_b32_e32 v72, 16, v142
	v_and_b32_e32 v73, 0xffff0000, v142
	v_lshlrev_b32_e32 v76, 16, v144
	v_and_b32_e32 v77, 0xffff0000, v144
	v_lshlrev_b32_e32 v74, 16, v140
	v_and_b32_e32 v75, 0xffff0000, v140
	v_pk_add_f32 v[72:73], v[72:73], v[76:77]
	s_waitcnt vmcnt(2)
	v_lshlrev_b32_e32 v78, 16, v156
	v_pk_fma_f32 v[72:73], v[72:73], 0.5, v[74:75] op_sel_hi:[1,0,1] neg_lo:[0,0,1] neg_hi:[0,0,1]
	v_and_b32_e32 v79, 0xffff0000, v156
	v_pk_fma_f32 v[72:73], v[0:1], v[72:73], v[74:75]
	v_lshlrev_b32_e32 v74, 16, v154
	v_and_b32_e32 v75, 0xffff0000, v154
	v_lshlrev_b32_e32 v76, 16, v152
	v_and_b32_e32 v77, 0xffff0000, v152
	v_pk_add_f32 v[74:75], v[74:75], v[78:79]
	s_waitcnt vmcnt(1)
	v_cvt_f32_f16_e32 v21, v158
	v_pk_fma_f32 v[74:75], v[74:75], 0.5, v[76:77] op_sel_hi:[1,0,1] neg_lo:[0,0,1] neg_hi:[0,0,1]
	v_lshlrev_b32_e32 v80, 16, v145
	v_pk_fma_f32 v[76:77], v[8:9], v[74:75], v[76:77]
	v_lshlrev_b32_e32 v74, 16, v143
	v_and_b32_e32 v75, 0xffff0000, v143
	v_and_b32_e32 v81, 0xffff0000, v145
	v_lshlrev_b32_e32 v78, 16, v141
	v_and_b32_e32 v79, 0xffff0000, v141
	v_pk_add_f32 v[74:75], v[74:75], v[80:81]
	v_cvt_f32_f16_sdwa v84, v158 dst_sel:DWORD dst_unused:UNUSED_PAD src0_sel:WORD_1
	v_pk_fma_f32 v[74:75], v[74:75], 0.5, v[78:79] op_sel_hi:[1,0,1] neg_lo:[0,0,1] neg_hi:[0,0,1]
	v_lshlrev_b32_e32 v82, 16, v157
	v_pk_fma_f32 v[74:75], v[2:3], v[74:75], v[78:79]
	v_lshlrev_b32_e32 v78, 16, v155
	v_and_b32_e32 v79, 0xffff0000, v155
	v_and_b32_e32 v83, 0xffff0000, v157
	v_cvt_f32_f16_e32 v88, v159
	v_lshlrev_b32_e32 v80, 16, v153
	v_and_b32_e32 v81, 0xffff0000, v153
	v_pk_add_f32 v[78:79], v[78:79], v[82:83]
	v_mul_f32_e32 v21, 0xbf1b4598, v21
	v_pk_fma_f32 v[78:79], v[78:79], 0.5, v[80:81] op_sel_hi:[1,0,1] neg_lo:[0,0,1] neg_hi:[0,0,1]
	v_mul_f32_e32 v21, 0x3fb8aa3b, v21
	v_cvt_f32_f16_sdwa v89, v159 dst_sel:DWORD dst_unused:UNUSED_PAD src0_sel:WORD_1
	v_pk_fma_f32 v[78:79], v[10:11], v[78:79], v[80:81]
	v_exp_f32_e32 v80, v21
	v_mul_f32_e32 v21, 0xbf1b4598, v84
	v_mul_f32_e32 v21, 0x3fb8aa3b, v21
	v_lshlrev_b32_e32 v82, 16, v148
	v_and_b32_e32 v83, 0xffff0000, v148
	v_lshlrev_b32_e32 v86, 16, v150
	v_and_b32_e32 v87, 0xffff0000, v150
	v_exp_f32_e32 v81, v21
	v_lshlrev_b32_e32 v84, 16, v146
	v_and_b32_e32 v85, 0xffff0000, v146
	v_pk_add_f32 v[82:83], v[82:83], v[86:87]
	v_mul_f32_e32 v21, 0xbf1b4598, v88
	v_pk_fma_f32 v[82:83], v[82:83], 0.5, v[84:85] op_sel_hi:[1,0,1] neg_lo:[0,0,1] neg_hi:[0,0,1]
	v_mul_f32_e32 v21, 0x3fb8aa3b, v21
	v_pk_fma_f32 v[96:97], v[4:5], v[82:83], v[84:85]
	v_exp_f32_e32 v82, v21
	v_mul_f32_e32 v21, 0xbf1b4598, v89
	v_lshlrev_b32_e32 v84, 16, v149
	v_and_b32_e32 v85, 0xffff0000, v149
	v_lshlrev_b32_e32 v88, 16, v151
	v_and_b32_e32 v89, 0xffff0000, v151
	v_lshlrev_b32_e32 v86, 16, v147
	v_and_b32_e32 v87, 0xffff0000, v147
	v_pk_add_f32 v[84:85], v[84:85], v[88:89]
	s_waitcnt vmcnt(0)
	v_cvt_f32_f16_sdwa v93, v160 dst_sel:DWORD dst_unused:UNUSED_PAD src0_sel:WORD_1
	v_pk_fma_f32 v[84:85], v[84:85], 0.5, v[86:87] op_sel_hi:[1,0,1] neg_lo:[0,0,1] neg_hi:[0,0,1]
	v_cvt_f32_f16_e32 v92, v160
	v_pk_fma_f32 v[94:95], v[6:7], v[84:85], v[86:87]
	v_pk_mul_f32 v[84:85], v[12:13], v[96:97]
	v_pk_mul_f32 v[88:89], v[14:15], v[94:95]
	v_pk_mul_f32 v[86:87], v[84:85], v[84:85]
	v_pk_mul_f32 v[90:91], v[88:89], v[88:89]
	v_add_f32_e32 v83, v86, v87
	v_add_f32_e32 v83, v90, v83
	v_add_f32_e32 v83, v91, v83
	v_cvt_f32_f16_sdwa v99, v161 dst_sel:DWORD dst_unused:UNUSED_PAD src0_sel:WORD_1
	v_cvt_f32_f16_e32 v98, v161
	v_add_f32_dpp v83, v83, v83 quad_perm:[1,0,3,2] row_mask:0xf bank_mask:0xf bound_ctrl:1
	v_mul_f32_e32 v21, 0x3fb8aa3b, v21
	s_bitcmp1_b32 s22, 0
	v_add_f32_dpp v83, v83, v83 quad_perm:[2,3,0,1] row_mask:0xf bank_mask:0xf bound_ctrl:1
	s_cselect_b32 s23, 0x2000, 0
	s_nop 0
	v_add_f32_dpp v83, v83, v83 row_half_mirror row_mask:0xf bank_mask:0xf bound_ctrl:1
	s_nop 1
	v_add_f32_dpp v83, v83, v83 row_mirror row_mask:0xf bank_mask:0xf bound_ctrl:1
	v_max_f32_e32 v83, 0x179abe15, v83
	v_rsq_f32_e32 v86, v83
	v_exp_f32_e32 v83, v21
	v_add_u32_e32 v21, s23, v67
	v_pk_mul_f32 v[90:91], v[84:85], v[86:87] op_sel_hi:[1,0]
	v_pk_mul_f32 v[100:101], v[88:89], v[86:87] op_sel_hi:[1,0]
	v_xor_b32_e32 v85, 0x80000000, v91
	v_xor_b32_e32 v84, 0x80000000, v90
	v_pk_mul_f32 v[88:89], v[90:91], v[92:93]
	v_pk_mul_f32 v[90:91], v[100:101], v[98:99]
	v_pk_add_f32 v[92:93], v[92:93], -1.0 op_sel_hi:[1,0]
	v_pk_add_f32 v[98:99], v[98:99], -1.0 op_sel_hi:[1,0]
	v_pk_fma_f32 v[92:93], v[16:17], v[92:93], 1.0 op_sel_hi:[1,1,0]
	v_pk_fma_f32 v[98:99], v[18:19], v[98:99], 1.0 op_sel_hi:[1,1,0]
	v_xor_b32_e32 v86, 0x80000000, v100
	v_xor_b32_e32 v87, 0x80000000, v101
	v_pk_mul_f32 v[94:95], v[94:95], v[98:99]
	v_pk_mul_f32 v[92:93], v[96:97], v[92:93]
	ds_write_b128 v67, v[80:83]
	ds_write_b128 v67, v[84:87] offset:8192
	ds_write_b128 v67, v[88:91] offset:16384
	ds_write_b128 v67, v[92:95] offset:24576
	ds_write_b128 v67, v[72:75] offset:32768
	ds_write_b128 v21, v[76:79] offset:40960
	v_add_u32_e32 v67, 0x1000, v67
	s_waitcnt lgkmcnt(0)
	s_barrier
	s_bfe_u32 s96, s62, 0x20006
	s_lshl_b32 s100, s96, 11
	v_lshl_add_u32 v72, v224, 2, s100
	s_and_b32 s97, s96, 1
	s_mul_i32 s97, s97, 0x2700
	s_mov_b32 s101, 0x1c000
	s_mov_b32 s100, 0x6100
	s_bitcmp0_b32 s65, 0
	s_cselect_b32 s101, 0xe000, s101
	s_cselect_b32 s100, 0x4e00, s100
	s_cmp_gt_u32 s96, 1
	s_cselect_b32 s100, s100, 0
	s_add_i32 s97, s97, s101
	s_add_i32 s97, s97, s100
	ds_read_b32 v80, v72
	ds_read_b32 v81, v72 offset:256
	ds_read_b32 v82, v72 offset:512
	ds_read_b32 v83, v72 offset:768
	ds_read_b32 v84, v72 offset:1024
	ds_read_b32 v85, v72 offset:1280
	ds_read_b32 v86, v72 offset:1536
	ds_read_b32 v87, v72 offset:1792
	ds_read_b32 v88, v72 offset:8192
	ds_read_b32 v89, v72 offset:8448
	ds_read_b32 v90, v72 offset:8704
	ds_read_b32 v91, v72 offset:8960
	ds_read_b32 v92, v72 offset:9216
	ds_read_b32 v93, v72 offset:9472
	ds_read_b32 v94, v72 offset:9728
	ds_read_b32 v95, v72 offset:9984
	ds_read_b32 v96, v72 offset:32768
	ds_read_b32 v97, v72 offset:33024
	ds_read_b32 v98, v72 offset:33280
	ds_read_b32 v99, v72 offset:33536
	ds_read_b32 v100, v72 offset:33792
	ds_read_b32 v101, v72 offset:34048
	ds_read_b32 v102, v72 offset:34304
	ds_read_b32 v103, v72 offset:34560
	v_and_b32_e32 v74, 3, v224
	v_bfe_u32 v75, v224, 2, 2
	v_lshrrev_b32_e32 v76, 4, v224
	v_lshlrev_b32_e32 v74, 2, v74
	v_lshl_add_u32 v74, v75, 8, v74
	v_lshl_add_u32 v74, v76, 10, v74
	s_add_i32 s100, s97, 0x0
	v_add_u32_e32 v74, s100, v74
	v_xor_b32_e32 v76, 0, v75
	v_xor_b32_e32 v77, 1, v75
	v_xor_b32_e32 v78, 2, v75
	v_xor_b32_e32 v79, 3, v75
	v_lshl_add_u32 v76, v76, 4, v74
	v_lshl_add_u32 v77, v77, 4, v74
	v_lshl_add_u32 v78, v78, 4, v74
	v_lshl_add_u32 v79, v79, 4, v74
	s_waitcnt lgkmcnt(15)
	v_mov_b32_e32 v104, v80
	v_mul_f32_e32 v105, v104, v81
	v_mul_f32_e32 v106, v105, v82
	v_mul_f32_e32 v107, v106, v83
	v_mul_f32_e32 v108, v107, v84
	v_mul_f32_e32 v109, v108, v85
	v_mul_f32_e32 v110, v109, v86
	v_mul_f32_e32 v111, v110, v87
	v_mov_b32_e32 v112, v88
	s_waitcnt lgkmcnt(14)
	v_mul_f32_e32 v113, v104, v89
	s_waitcnt lgkmcnt(13)
	v_mul_f32_e32 v114, v105, v90
	s_waitcnt lgkmcnt(12)
	v_mul_f32_e32 v115, v106, v91
	s_waitcnt lgkmcnt(11)
	v_mul_f32_e32 v116, v107, v92
	s_waitcnt lgkmcnt(10)
	v_mul_f32_e32 v117, v108, v93
	s_waitcnt lgkmcnt(9)
	v_mul_f32_e32 v118, v109, v94
	s_waitcnt lgkmcnt(8)
	v_mul_f32_e32 v119, v110, v95
	s_waitcnt lgkmcnt(7)
	v_mul_f32_e32 v120, v104, v96
	s_waitcnt lgkmcnt(6)
	v_mul_f32_e32 v121, v105, v97
	s_waitcnt lgkmcnt(5)
	v_mul_f32_e32 v122, v106, v98
	s_waitcnt lgkmcnt(4)
	v_mul_f32_e32 v123, v107, v99
	s_waitcnt lgkmcnt(3)
	v_mul_f32_e32 v124, v108, v100
	s_waitcnt lgkmcnt(2)
	v_mul_f32_e32 v125, v109, v101
	s_waitcnt lgkmcnt(1)
	v_mul_f32_e32 v126, v110, v102
	s_waitcnt lgkmcnt(0)
	v_mul_f32_e32 v127, v111, v103
	ds_write_b32 v76, v112
	ds_write_b32 v77, v113
	ds_write_b32 v78, v114
	ds_write_b32 v79, v115
	ds_write_b32 v76, v116 offset:64
	ds_write_b32 v77, v117 offset:64
	ds_write_b32 v78, v118 offset:64
	ds_write_b32 v79, v119 offset:64
	ds_write_b32 v76, v120 offset:128
	ds_write_b32 v77, v121 offset:128
	ds_write_b32 v78, v122 offset:128
	ds_write_b32 v79, v123 offset:128
	ds_write_b32 v76, v124 offset:192
	ds_write_b32 v77, v125 offset:192
	ds_write_b32 v78, v126 offset:192
	ds_write_b32 v79, v127 offset:192

.Lmy_ck_drE_h:
	s_waitcnt lgkmcnt(0)
	s_barrier
	s_bfe_u32 s96, s62, 0x20006
	s_and_b32 s97, s96, 1
	s_mul_i32 s97, s97, 0x2700
	s_mov_b32 s101, 0x1c000
	s_mov_b32 s100, 0x6100
	s_bitcmp0_b32 s65, 0
	s_cselect_b32 s101, 0xe000, s101
	s_cselect_b32 s100, 0x4e00, s100
	s_cmp_gt_u32 s96, 1
	s_cselect_b32 s100, s100, 0
	s_add_i32 s97, s97, s101
	s_add_i32 s97, s97, s100
	s_mov_b32 s96, s97
	v_and_b32_e32 v72, 3, v233
	v_lshrrev_b32_e32 v73, 2, v233
	v_lshlrev_b32_e32 v72, 2, v72
	v_lshl_add_u32 v72, v73, 8, v72
	v_lshl_add_u32 v72, v234, 6, v72
	s_add_i32 s97, s96, 0x1000
	v_add_u32_e32 v78, s97, v72
	v_xor_b32_e32 v79, v224, v234
	v_lshl_add_u32 v79, v79, 4, s96
	ds_read_b128 v[96:99], v79
	ds_read_b128 v[100:103], v79 offset:1024
	ds_read_b128 v[104:107], v79 offset:2048
	ds_read_b128 v[108:111], v79 offset:3072
	ds_read_b32 v80, v78
	ds_read_b32 v81, v78 offset:16
	ds_read_b32 v82, v78 offset:32
	ds_read_b32 v83, v78 offset:48
	ds_read_b32 v84, v78 offset:1024
	ds_read_b32 v85, v78 offset:1040
	ds_read_b32 v86, v78 offset:1056
	ds_read_b32 v87, v78 offset:1072
	ds_read_b32 v88, v78 offset:2048
	ds_read_b32 v89, v78 offset:2064
	ds_read_b32 v90, v78 offset:2080
	ds_read_b32 v91, v78 offset:2096
	ds_read_b32 v92, v78 offset:3072
	ds_read_b32 v93, v78 offset:3088
	ds_read_b32 v94, v78 offset:3104
	ds_read_b32 v95, v78 offset:3120
	v_lshl_add_u32 v74, v224, 2, s96
	ds_write_b32 v74, v235 offset:9728
	v_add_u32_e32 v75, -1, v233
	v_mov_b32_e32 v76, -1
	v_cndmask_b32_e64 v75, v76, v75, s[98:99]
	v_cmp_lt_u32_e64 s[100:101], 7, v233
	v_add_u32_e32 v76, -8, v233
	v_and_b32_e32 v77, 1, v234
	v_cndmask_b32_e64 v75, v75, v76, s[100:101]
	v_lshlrev_b32_e32 v77, 2, v77
	v_sub_u32_e32 v76, v75, v77
	v_lshlrev_b32_e32 v77, 2, v234
	v_sub_u32_e32 v77, v233, v77
	v_add_u32_e32 v77, -1, v77
	s_waitcnt lgkmcnt(15)
	v_mfma_f32_16x16x4_f32 v[244:247], v80, v96, 0
	v_mfma_f32_16x16x4_f32 v[240:243], v81, v97, 0
	s_waitcnt lgkmcnt(14)
	v_mfma_f32_16x16x4_f32 v[244:247], v82, v98, v[244:247]
	s_waitcnt lgkmcnt(13)
	v_mfma_f32_16x16x4_f32 v[240:243], v83, v99, v[240:243]
	s_waitcnt lgkmcnt(12)
	v_mfma_f32_16x16x4_f32 v[244:247], v84, v100, v[244:247]
	s_waitcnt lgkmcnt(11)
	v_mfma_f32_16x16x4_f32 v[240:243], v85, v101, v[240:243]
	s_waitcnt lgkmcnt(10)
	v_mfma_f32_16x16x4_f32 v[244:247], v86, v102, v[244:247]
	s_waitcnt lgkmcnt(9)
	v_mfma_f32_16x16x4_f32 v[240:243], v87, v103, v[240:243]
	s_waitcnt lgkmcnt(8)
	v_mfma_f32_16x16x4_f32 v[244:247], v88, v104, v[244:247]
	s_waitcnt lgkmcnt(7)
	v_mfma_f32_16x16x4_f32 v[240:243], v89, v105, v[240:243]
	s_waitcnt lgkmcnt(6)
	v_mfma_f32_16x16x4_f32 v[244:247], v90, v106, v[244:247]
	s_waitcnt lgkmcnt(5)
	v_mfma_f32_16x16x4_f32 v[240:243], v91, v107, v[240:243]
	s_waitcnt lgkmcnt(4)
	v_mfma_f32_16x16x4_f32 v[244:247], v92, v108, v[244:247]
	s_waitcnt lgkmcnt(3)
	v_mfma_f32_16x16x4_f32 v[240:243], v93, v109, v[240:243]
	s_waitcnt lgkmcnt(2)
	v_mfma_f32_16x16x4_f32 v[244:247], v94, v110, v[244:247]
	s_waitcnt lgkmcnt(1)
	v_mfma_f32_16x16x4_f32 v[240:243], v95, v111, v[240:243]
	s_nop 9
	v_add_f32_e32 v244, v244, v240
	v_add_f32_e32 v245, v245, v241
	v_add_f32_e32 v246, v246, v242
	v_add_f32_e32 v247, v247, v243
	v_cmp_le_i32_e64 s[96:97], 0, v76
	v_cmp_le_i32_e64 s[100:101], 1, v76
	s_nop 0
	v_cndmask_b32_e64 v128, 0, v244, s[96:97]
	v_cndmask_b32_e64 v129, 0, v245, s[100:101]
	v_cmp_le_i32_e64 s[96:97], 2, v76
	v_cmp_le_i32_e64 s[100:101], 3, v76
	s_nop 0
	v_cndmask_b32_e64 v130, 0, v246, s[96:97]
	v_cndmask_b32_e64 v131, 0, v247, s[100:101]
	s_bfe_u32 s96, s62, 0x20006
	s_and_b32 s97, s96, 1
	s_mul_i32 s97, s97, 0x2700
	s_mov_b32 s101, 0x1c000
	s_mov_b32 s100, 0x6100
	s_bitcmp0_b32 s65, 0
	s_cselect_b32 s101, 0xe000, s101
	s_cselect_b32 s100, 0x4e00, s100
	s_cmp_gt_u32 s96, 1
	s_cselect_b32 s100, s100, 0
	s_add_i32 s97, s97, s101
	s_add_i32 s97, s97, s100
	v_xor_b32_e32 v74, v224, v234
	v_lshl_add_u32 v74, v74, 4, s97
	ds_write_b128 v74, v[128:131] offset:8448
	v_lshlrev_b32_e32 v75, 7, v234
	v_lshl_add_u32 v75, v233, 2, v75
	v_add_u32_e32 v75, s97, v75
	v_cmp_le_i32_e64 s[96:97], 0, v77
	v_cmp_le_i32_e64 s[100:101], 1, v77
	s_nop 0
	v_cndmask_b32_e64 v132, 0, v244, s[96:97]
	v_cndmask_b32_e64 v133, 0, v245, s[100:101]
	v_cmp_le_i32_e64 s[96:97], 2, v77
	v_cmp_le_i32_e64 s[100:101], 3, v77
	s_nop 0
	v_cndmask_b32_e64 v134, 0, v246, s[96:97]
	v_cndmask_b32_e64 v135, 0, v247, s[100:101]
	s_mov_b64 exec, 0x00ff00ff
	ds_write_b32 v75, v132 offset:9472
	ds_write_b32 v75, v133 offset:9504
	ds_write_b32 v75, v134 offset:9536
	ds_write_b32 v75, v135 offset:9568
	s_mov_b64 exec, -1
	s_branch .LBB0_655
